# retstate: K/V prefetch loads made unconditional (clamped), vmcnt waits exact for 2-step prefetch distance
# baseline (speedup 1.0000x reference)
.LBB0_709:
	s_waitcnt vmcnt(0)
	s_add_i32 s14, s14, s28
	s_cmpk_gt_i32 s14, 0xff
	s_mov_b32 s11, 0x3f2aaaab
	s_mov_b32 s12, 0x3f317218
	s_cbranch_scc1 .LBB0_716
.LBB0_710:
	s_bfe_u32 s15, s14, 0x20002
	s_nop 4
	v_cvt_f32_ubyte0_e32 v0, s15
	v_sub_f32_e32 v0, 0xc0a00000, v0
	v_cmp_gt_f32_e32 vcc, s20, v0
	s_ashr_i32 s10, s14, 4
	s_and_b64 s[6:7], vcc, exec
	v_cndmask_b32_e32 v1, 0, v228, vcc
	v_add_f32_e32 v0, v0, v1
	v_exp_f32_e32 v1, v0
	s_cselect_b32 s6, 0xffffffc0, 0
	s_lshl_b32 s88, s15, 8
	s_bfe_i32 s17, s14, 0x10001
	v_ldexp_f32 v1, v1, s6
	v_sub_f32_e32 v4, 1.0, v1
	v_add_f32_e32 v2, -1.0, v4
	v_sub_f32_e32 v3, v2, v4
	v_add_f32_e32 v3, 1.0, v3
	v_sub_f32_e64 v2, -v1, v2
	v_add_f32_e32 v5, v2, v3
	v_frexp_mant_f32_e32 v6, v4
	v_cvt_f64_f32_e32 v[2:3], v4
	v_frexp_exp_i32_f64_e32 v2, v[2:3]
	v_cmp_gt_f32_e32 vcc, s11, v6
	s_ashr_i32 s11, s10, 31
	s_lshl_b64 s[6:7], s[10:11], 11
	v_subbrev_co_u32_e32 v2, vcc, 0, v2, vcc
	v_sub_u32_e32 v3, 0, v2
	v_ldexp_f32 v4, v4, v3
	v_ldexp_f32 v3, v5, v3
	v_add_f32_e32 v5, -1.0, v4
	v_add_f32_e32 v8, 1.0, v4
	v_add_f32_e32 v6, 1.0, v5
	v_add_f32_e32 v9, -1.0, v8
	v_sub_f32_e32 v6, v4, v6
	v_sub_f32_e32 v4, v4, v9
	v_add_f32_e32 v6, v3, v6
	v_add_f32_e32 v3, v3, v4
	v_add_f32_e32 v4, v8, v3
	v_rcp_f32_e32 v9, v4
	v_add_f32_e32 v7, v5, v6
	v_sub_f32_e32 v5, v7, v5
	v_sub_f32_e32 v5, v6, v5
	v_sub_f32_e32 v6, v4, v8
	v_sub_f32_e32 v3, v3, v6
	v_mul_f32_e32 v6, v7, v9
	v_mul_f32_e32 v8, v4, v6
	v_fma_f32 v10, v6, v4, -v8
	v_fmac_f32_e32 v10, v6, v3
	v_add_f32_e32 v11, v8, v10
	v_sub_f32_e32 v12, v7, v11
	v_sub_f32_e32 v7, v7, v12
	v_sub_f32_e32 v8, v11, v8
	v_sub_f32_e32 v7, v7, v11
	v_add_f32_e32 v5, v5, v7
	v_sub_f32_e32 v7, v8, v10
	v_add_f32_e32 v5, v7, v5
	v_add_f32_e32 v7, v12, v5
	v_mul_f32_e32 v8, v9, v7
	v_mul_f32_e32 v10, v4, v8
	v_fma_f32 v4, v8, v4, -v10
	v_fmac_f32_e32 v4, v8, v3
	v_sub_f32_e32 v3, v12, v7
	v_add_f32_e32 v3, v5, v3
	v_add_f32_e32 v5, v10, v4
	v_sub_f32_e32 v11, v7, v5
	v_sub_f32_e32 v7, v7, v11
	v_sub_f32_e32 v10, v5, v10
	v_sub_f32_e32 v5, v7, v5
	v_add_f32_e32 v3, v3, v5
	v_sub_f32_e32 v4, v10, v4
	v_cvt_f32_i32_e32 v2, v2
	v_add_f32_e32 v3, v4, v3
	v_add_f32_e32 v4, v6, v8
	v_add_f32_e32 v3, v11, v3
	v_sub_f32_e32 v5, v4, v6
	v_mul_f32_e32 v3, v9, v3
	v_sub_f32_e32 v5, v8, v5
	v_add_f32_e32 v3, v5, v3
	v_mul_f32_e32 v8, 0x3f317218, v2
	v_add_f32_e32 v5, v4, v3
	v_fma_f32 v9, v2, s12, -v8
	v_mul_f32_e32 v6, v5, v5
	v_fmac_f32_e32 v9, 0xb102e308, v2
	v_sub_f32_e32 v2, v5, v4
	v_fmamk_f32 v7, v6, 0x3e9b6dac, v222
	v_sub_f32_e32 v2, v3, v2
	v_add_f32_e32 v3, v8, v9
	v_fmaak_f32 v7, v6, v7, 0x3f2aaada
	v_sub_f32_e32 v4, v3, v8
	v_ldexp_f32 v8, v5, 1
	v_mul_f32_e32 v5, v5, v6
	v_mul_f32_e32 v5, v5, v7
	v_add_f32_e32 v6, v8, v5
	v_sub_f32_e32 v7, v6, v8
	v_ldexp_f32 v2, v2, 1
	v_sub_f32_e32 v5, v5, v7
	v_add_f32_e32 v2, v2, v5
	v_add_f32_e32 v5, v6, v2
	v_sub_f32_e32 v6, v5, v6
	v_sub_f32_e32 v2, v2, v6
	v_add_f32_e32 v6, v3, v5
	v_sub_f32_e32 v7, v6, v3
	v_sub_f32_e32 v8, v6, v7
	v_sub_f32_e32 v4, v9, v4
	v_sub_f32_e32 v3, v3, v8
	v_sub_f32_e32 v5, v5, v7
	v_add_f32_e32 v3, v5, v3
	v_add_f32_e32 v5, v4, v2
	v_sub_f32_e32 v7, v5, v4
	v_sub_f32_e32 v8, v5, v7
	v_sub_f32_e32 v4, v4, v8
	v_sub_f32_e32 v2, v2, v7
	v_add_f32_e32 v3, v5, v3
	v_add_f32_e32 v2, v2, v4
	v_add_f32_e32 v4, v6, v3
	v_sub_f32_e32 v5, v4, v6
	v_sub_f32_e32 v3, v3, v5
	v_add_f32_e32 v2, v2, v3
	v_add_f32_e32 v2, v4, v2
	v_cmp_nlt_f32_e32 vcc, 1.0, v1
	v_mov_b64_e32 v[4:5], s[8:9]
	v_mov_b32_e32 v103, v33
	v_cndmask_b32_e32 v2, v225, v2, vcc
	v_cmp_neq_f32_e32 vcc, 1.0, v1
	s_mov_b32 s24, 0xb0000
	s_mov_b32 s25, 0x108000
	v_cndmask_b32_e32 v8, v229, v2, vcc
	v_lshl_add_u64 v[2:3], s[6:7], 0, v[98:99]
	v_mad_u64_u32 v[6:7], s[12:13], v2, s97, v[4:5]
	v_mad_i32_i24 v7, v3, s97, v7
	v_lshl_add_u64 v[2:3], v[6:7], 0, s[88:89]
	v_lshl_add_u64 v[6:7], s[6:7], 0, v[100:101]
	v_mad_u64_u32 v[4:5], s[6:7], v6, s97, v[4:5]
	s_lshl_b32 s6, s14, 6
	v_mad_i32_i24 v5, v7, s97, v5
	s_and_b32 s11, s6, 64
	v_lshl_add_u64 v[4:5], v[4:5], 0, s[88:89]
	s_lshl_b32 s88, s11, 1
	s_and_b32 s6, s14, 2
	s_cmp_eq_u32 s6, 0
	s_cselect_b64 s[6:7], -1, 0
	s_and_b64 s[12:13], s[6:7], exec
	s_mov_b32 s12, 0x365d0000
	v_lshl_add_u64 v[4:5], v[4:5], 0, s[88:89]
	s_cselect_b32 s23, s12, 0x385d0000
	v_lshl_add_u64 v[2:3], v[2:3], 0, v[32:33]
	s_mov_b64 s[12:13], 0x2000
	v_lshl_add_u64 v[108:109], v[2:3], 0, s[12:13]
	v_lshl_add_u64 v[2:3], v[4:5], 0, v[102:103]
	s_mov_b64 s[12:13], 0x2400
	v_lshl_add_u64 v[110:111], v[2:3], 0, s[12:13]
	s_mov_b32 s12, 0x160000
	s_cselect_b32 s16, s12, 0x1340000
	s_add_u32 s12, s0, s23
	s_addc_u32 s13, s1, 0
	s_and_b32 s88, s17, 0x14a0000
	v_lshl_add_u64 v[2:3], v[108:109], 0, s[88:89]
	s_mov_b32 s23, 0x58000
	v_add_co_u32_e32 v4, vcc, s23, v2
	s_mov_b32 s17, s89
	s_nop 0
	v_addc_co_u32_e32 v5, vcc, 0, v3, vcc
	global_load_dwordx4 v[16:19], v[2:3], off
	global_load_dwordx4 v[20:23], v[4:5], off
	v_add_co_u32_e32 v4, vcc, s24, v2
	v_cndmask_b32_e64 v6, v98, v123, s[6:7]
	s_nop 0
	v_addc_co_u32_e32 v5, vcc, 0, v3, vcc
	v_add_co_u32_e32 v2, vcc, s25, v2
	v_cvt_f32_i32_e32 v6, v6
	s_nop 0
	v_addc_co_u32_e32 v3, vcc, 0, v3, vcc
	global_load_dwordx4 v[24:27], v[4:5], off
	global_load_dwordx4 v[28:31], v[2:3], off
	v_lshl_add_u64 v[2:3], v[110:111], 0, s[88:89]
	v_add_co_u32_e32 v4, vcc, s24, v2
	v_mov_b32_e32 v105, v33
	s_nop 0
	v_addc_co_u32_e32 v5, vcc, 0, v3, vcc
	global_load_dwordx4 v[42:45], v[2:3], off
	global_load_dwordx4 v[46:49], v[4:5], off
	v_lshl_add_u64 v[2:3], v[108:109], 0, s[16:17]
	v_add_co_u32_e32 v4, vcc, s23, v2
	v_mov_b32_e32 v0, 0
	s_nop 0
	v_addc_co_u32_e32 v5, vcc, 0, v3, vcc
	global_load_dwordx4 v[34:37], v[2:3], off
	global_load_dwordx4 v[38:41], v[4:5], off
	v_add_co_u32_e32 v4, vcc, s24, v2
	v_mov_b32_e32 v107, v33
	s_nop 0
	v_addc_co_u32_e32 v5, vcc, 0, v3, vcc
	v_add_co_u32_e32 v2, vcc, s25, v2
	v_mov_b32_e32 v7, v0
	s_nop 0
	v_addc_co_u32_e32 v3, vcc, 0, v3, vcc
	global_load_dwordx4 v[50:53], v[4:5], off
	global_load_dwordx4 v[54:57], v[2:3], off
	v_lshl_add_u64 v[2:3], v[110:111], 0, s[16:17]
	v_add_co_u32_e32 v4, vcc, s24, v2
	s_mov_b32 s16, 0x33800000
	s_nop 0
	v_addc_co_u32_e32 v5, vcc, 0, v3, vcc
	global_load_dwordx4 v[58:61], v[2:3], off
	global_load_dwordx4 v[62:65], v[4:5], off
	v_cmp_gt_f32_e32 vcc, s16, v1
	v_cndmask_b32_e64 v3, v124, v125, s[6:7]
	v_cvt_f32_i32_e32 v3, v3
	v_cndmask_b32_e64 v1, v8, -v1, vcc
	v_mul_f32_e32 v1, 0x3fb8aa3b, v1
	v_mul_f32_e32 v2, v1, v6
	v_cmp_gt_f32_e32 vcc, s20, v2
	v_mul_f32_e32 v4, 0x43000000, v1
	v_mov_b32_e32 v8, v0
	v_cndmask_b32_e32 v2, 0, v228, vcc
	v_fmac_f32_e32 v2, v1, v6
	v_exp_f32_e32 v2, v2
	v_cndmask_b32_e32 v5, 0, v223, vcc
	v_mov_b32_e32 v9, v0
	v_mov_b32_e32 v10, v0
	v_ldexp_f32 v103, v2, v5
	v_cndmask_b32_e64 v5, v126, v127, s[6:7]
	v_cvt_f32_i32_e32 v5, v5
	v_mul_f32_e32 v2, v1, v3
	v_cmp_gt_f32_e32 vcc, s20, v2
	v_mov_b32_e32 v11, v0
	v_mul_f32_e32 v6, v1, v5
	v_cndmask_b32_e32 v2, 0, v228, vcc
	v_fmac_f32_e32 v2, v1, v3
	v_cndmask_b32_e32 v3, 0, v223, vcc
	v_cmp_gt_f32_e32 vcc, s20, v6
	v_exp_f32_e32 v2, v2
	v_mov_b32_e32 v12, v0
	v_cndmask_b32_e32 v6, 0, v228, vcc
	v_fmac_f32_e32 v6, v1, v5
	v_exp_f32_e32 v5, v6
	v_cndmask_b32_e64 v6, v128, v129, s[6:7]
	v_cvt_f32_i32_e32 v6, v6
	v_ldexp_f32 v139, v2, v3
	v_cndmask_b32_e32 v2, 0, v223, vcc
	v_ldexp_f32 v140, v5, v2
	v_mul_f32_e32 v2, v1, v6
	v_cmp_gt_f32_e32 vcc, s20, v2
	v_mov_b32_e32 v5, v0
	v_mov_b32_e32 v13, v0
	v_cndmask_b32_e32 v2, 0, v228, vcc
	v_fmac_f32_e32 v2, v1, v6
	v_exp_f32_e32 v2, v2
	v_cndmask_b32_e32 v3, 0, v223, vcc
	v_cmp_gt_f32_e32 vcc, s20, v4
	s_and_b64 s[16:17], vcc, exec
	v_ldexp_f32 v141, v2, v3
	v_cndmask_b32_e32 v4, 0, v228, vcc
	v_fmac_f32_e32 v4, 0x43000000, v1
	v_exp_f32_e32 v1, v4
	v_add_u32_e32 v2, s11, v118
	v_ashrrev_i32_e32 v3, 31, v2
	s_cselect_b32 s16, 0xffffffc0, 0
	s_lshl_b32 s10, s10, 2
	v_lshlrev_b64 v[2:3], 8, v[2:3]
	s_or_b32 s10, s10, s15
	v_lshl_add_u64 v[2:3], s[12:13], 0, v[2:3]
	v_ldexp_f32 v112, v1, s16
	s_ashr_i32 s11, s10, 31
	v_lshl_add_u64 v[2:3], v[2:3], 0, v[104:105]
	s_lshl_b64 s[10:11], s[10:11], 4
	v_lshl_add_u64 v[114:115], v[2:3], 0, v[106:107]
	v_mov_b32_e32 v116, v112
	v_mov_b32_e32 v117, v112
	s_mov_b32 s12, 3
	s_mov_b32 s13, 12
	v_mov_b32_e32 v1, v0
	v_mov_b32_e32 v2, v0
	v_mov_b32_e32 v3, v0
	v_mov_b32_e32 v4, v0
	v_mov_b32_e32 v6, v0
	v_mov_b32_e32 v14, v0
	v_mov_b32_e32 v15, v0
	s_waitcnt vmcnt(0)
	s_barrier
	s_branch .LBB0_712

.LBB0_712:
	s_waitcnt vmcnt(19)
	v_lshlrev_b32_e32 v66, 16, v16
	v_and_b32_e32 v67, 0xffff0000, v16
	v_lshlrev_b32_e32 v68, 16, v17
	v_and_b32_e32 v69, 0xffff0000, v17
	v_lshlrev_b32_e32 v70, 16, v18
	v_and_b32_e32 v71, 0xffff0000, v18
	v_lshlrev_b32_e32 v72, 16, v19
	v_and_b32_e32 v73, 0xffff0000, v19
	v_mul_f32_e32 v66, v103, v66
	v_mul_f32_e32 v67, v103, v67
	v_mul_f32_e32 v68, v103, v68
	v_mul_f32_e32 v69, v103, v69
	v_mul_f32_e32 v70, v103, v70
	v_mul_f32_e32 v71, v103, v71
	v_mul_f32_e32 v72, v103, v72
	v_mul_f32_e32 v73, v103, v73
	v_cvt_pk_bf16_f32 v66, v66, v67
	v_cvt_pk_bf16_f32 v67, v68, v69
	v_cvt_pk_bf16_f32 v68, v70, v71
	v_cvt_pk_bf16_f32 v69, v72, v73
	v_add_u32_e32 v70, 0, v130
	ds_write_b128 v70, v[66:69]
	s_waitcnt vmcnt(18)
	v_lshlrev_b32_e32 v66, 16, v20
	v_and_b32_e32 v67, 0xffff0000, v20
	v_lshlrev_b32_e32 v68, 16, v21
	v_and_b32_e32 v69, 0xffff0000, v21
	v_lshlrev_b32_e32 v70, 16, v22
	v_and_b32_e32 v71, 0xffff0000, v22
	v_lshlrev_b32_e32 v72, 16, v23
	v_and_b32_e32 v73, 0xffff0000, v23
	v_mul_f32_e32 v66, v139, v66
	v_mul_f32_e32 v67, v139, v67
	v_mul_f32_e32 v68, v139, v68
	v_mul_f32_e32 v69, v139, v69
	v_mul_f32_e32 v70, v139, v70
	v_mul_f32_e32 v71, v139, v71
	v_mul_f32_e32 v72, v139, v72
	v_mul_f32_e32 v73, v139, v73
	v_cvt_pk_bf16_f32 v66, v66, v67
	v_cvt_pk_bf16_f32 v67, v68, v69
	v_cvt_pk_bf16_f32 v68, v70, v71
	v_cvt_pk_bf16_f32 v69, v72, v73
	v_add_u32_e32 v70, 0, v131
	ds_write_b128 v70, v[66:69]
	s_waitcnt vmcnt(17)
	v_lshlrev_b32_e32 v66, 16, v24
	v_and_b32_e32 v67, 0xffff0000, v24
	v_lshlrev_b32_e32 v68, 16, v25
	v_and_b32_e32 v69, 0xffff0000, v25
	v_lshlrev_b32_e32 v70, 16, v26
	v_and_b32_e32 v71, 0xffff0000, v26
	v_lshlrev_b32_e32 v72, 16, v27
	v_and_b32_e32 v73, 0xffff0000, v27
	v_mul_f32_e32 v66, v140, v66
	v_mul_f32_e32 v67, v140, v67
	v_mul_f32_e32 v68, v140, v68
	v_mul_f32_e32 v69, v140, v69
	v_mul_f32_e32 v70, v140, v70
	v_mul_f32_e32 v71, v140, v71
	v_mul_f32_e32 v72, v140, v72
	v_mul_f32_e32 v73, v140, v73
	v_cvt_pk_bf16_f32 v66, v66, v67
	v_cvt_pk_bf16_f32 v67, v68, v69
	v_cvt_pk_bf16_f32 v68, v70, v71
	v_cvt_pk_bf16_f32 v69, v72, v73
	v_add_u32_e32 v70, 0, v132
	ds_write_b128 v70, v[66:69]
	s_waitcnt vmcnt(16)
	v_lshlrev_b32_e32 v66, 16, v28
	v_and_b32_e32 v67, 0xffff0000, v28
	v_lshlrev_b32_e32 v68, 16, v29
	v_and_b32_e32 v69, 0xffff0000, v29
	v_lshlrev_b32_e32 v70, 16, v30
	s_add_i32 s15, s12, -3
	v_and_b32_e32 v71, 0xffff0000, v30
	v_lshlrev_b32_e32 v72, 16, v31
	v_and_b32_e32 v73, 0xffff0000, v31
	v_mul_f32_e32 v66, v141, v66
	v_mul_f32_e32 v67, v141, v67
	v_mul_f32_e32 v68, v141, v68
	v_mul_f32_e32 v69, v141, v69
	v_mul_f32_e32 v70, v141, v70
	v_mul_f32_e32 v71, v141, v71
	v_mul_f32_e32 v72, v141, v72
	v_mul_f32_e32 v73, v141, v73
	v_cvt_pk_bf16_f32 v66, v66, v67
	v_cvt_pk_bf16_f32 v67, v68, v69
	v_cvt_pk_bf16_f32 v68, v70, v71
	v_cvt_pk_bf16_f32 v69, v72, v73
	v_add_u32_e32 v70, 0, v133
	s_cmp_lt_u32 s15, 14
	ds_write_b128 v70, v[66:69]
	s_waitcnt vmcnt(15)
	ds_write_b128 v138, v[42:45] offset:34816
	s_waitcnt vmcnt(14)
	ds_write_b128 v138, v[46:49] offset:52224
	s_waitcnt lgkmcnt(0)
	s_barrier
	s_add_i32 s23, s12, -1
	s_add_i32 s24, s13, 1
	s_and_b64 s[16:17], s[6:7], exec
	s_cselect_b32 s16, s23, s24
	s_min_i32 s16, s16, 15
	s_max_i32 s16, s16, 0
	s_mul_i32 s88, s16, 0x160000
	v_lshl_add_u64 v[24:25], v[108:109], 0, s[88:89]
	v_add_co_u32_e32 v20, vcc, 0x58000, v24
	v_lshl_add_u64 v[42:43], v[110:111], 0, s[88:89]
	s_nop 0
	v_addc_co_u32_e32 v21, vcc, 0, v25, vcc
	v_add_co_u32_e32 v26, vcc, 0xb0000, v24
	global_load_dwordx4 v[16:19], v[24:25], off
	s_nop 0
	global_load_dwordx4 v[20:23], v[20:21], off
	v_addc_co_u32_e32 v27, vcc, 0, v25, vcc
	v_add_co_u32_e32 v28, vcc, 0x108000, v24
	s_nop 1
	v_addc_co_u32_e32 v29, vcc, 0, v25, vcc
	v_add_co_u32_e32 v46, vcc, 0xb0000, v42
	global_load_dwordx4 v[24:27], v[26:27], off
	s_nop 0
	global_load_dwordx4 v[28:31], v[28:29], off
	v_addc_co_u32_e32 v47, vcc, 0, v43, vcc
	global_load_dwordx4 v[42:45], v[42:43], off
	s_nop 0
	global_load_dwordx4 v[46:49], v[46:47], off
.LBB0_714:
	s_add_i32 s23, s13, 3
	s_and_b64 s[16:17], s[6:7], exec
	s_cselect_b32 s16, s15, s23
	s_add_u32 s16, s10, s16
	s_addc_u32 s17, s11, 0
	s_lshl_b64 s[16:17], s[16:17], 15
	v_lshl_add_u64 v[66:67], v[114:115], 0, s[16:17]
	v_cvt_pk_bf16_f32 v68, v0, v1
	v_cvt_pk_bf16_f32 v69, v2, v3
	global_store_dwordx2 v[66:67], v[68:69], off
	v_cvt_pk_bf16_f32 v68, v4, v5
	v_cvt_pk_bf16_f32 v69, v6, v7
	global_store_dwordx2 v[66:67], v[68:69], off offset:16
	v_cvt_pk_bf16_f32 v68, v8, v9
	v_cvt_pk_bf16_f32 v69, v10, v11
	global_store_dwordx2 v[66:67], v[68:69], off offset:32
	v_cvt_pk_bf16_f32 v68, v12, v13
	v_cvt_pk_bf16_f32 v69, v14, v15
	global_store_dwordx2 v[66:67], v[68:69], off offset:48
	v_mov_b32_e32 v113, v112
	v_pk_mul_f32 v[14:15], v[112:113], v[14:15]
	v_pk_mul_f32 v[12:13], v[112:113], v[12:13]
	v_pk_mul_f32 v[10:11], v[112:113], v[10:11]
	v_pk_mul_f32 v[8:9], v[112:113], v[8:9]
	v_pk_mul_f32 v[6:7], v[112:113], v[6:7]
	v_pk_mul_f32 v[4:5], v[112:113], v[4:5]
	v_pk_mul_f32 v[2:3], v[112:113], v[2:3]
	v_pk_mul_f32 v[0:1], v[116:117], v[0:1]
	ds_read_b64_tr_b16 v[78:79], v119 offset:0
	ds_read_b64_tr_b16 v[80:81], v119 offset:1088
	ds_read_b64_tr_b16 v[74:75], v119 offset:4352
	ds_read_b64_tr_b16 v[76:77], v119 offset:5440
	ds_read_b64_tr_b16 v[70:71], v119 offset:8704
	ds_read_b64_tr_b16 v[72:73], v119 offset:9792
	ds_read_b64_tr_b16 v[66:67], v119 offset:13056
	ds_read_b64_tr_b16 v[68:69], v119 offset:14144
	s_waitcnt lgkmcnt(0)
	ds_read_b64_tr_b16 v[94:95], v120 offset:0
	ds_read_b64_tr_b16 v[96:97], v120 offset:1088
	ds_read_b64_tr_b16 v[90:91], v120 offset:4352
	ds_read_b64_tr_b16 v[92:93], v120 offset:5440
	ds_read_b64_tr_b16 v[86:87], v120 offset:8704
	ds_read_b64_tr_b16 v[88:89], v120 offset:9792
	ds_read_b64_tr_b16 v[82:83], v120 offset:13056
	ds_read_b64_tr_b16 v[84:85], v120 offset:14144
	s_waitcnt lgkmcnt(0)
	s_waitcnt vmcnt(19)
	v_lshlrev_b32_e32 v105, 16, v34
	v_and_b32_e32 v107, 0xffff0000, v34
	v_mfma_f32_32x32x16_bf16 v[0:15], v[78:81], v[94:97], v[0:15]
	v_lshlrev_b32_e32 v142, 16, v35
	v_and_b32_e32 v143, 0xffff0000, v35
	v_lshlrev_b32_e32 v144, 16, v36
	v_and_b32_e32 v145, 0xffff0000, v36
	v_mul_f32_e32 v105, v103, v105
	v_lshlrev_b32_e32 v146, 16, v37
	v_and_b32_e32 v147, 0xffff0000, v37
	v_mfma_f32_32x32x16_bf16 v[0:15], v[74:77], v[90:93], v[0:15]
	v_mul_f32_e32 v107, v103, v107
	v_mul_f32_e32 v148, v103, v142
	v_mul_f32_e32 v143, v103, v143
	v_mul_f32_e32 v144, v103, v144
	v_mul_f32_e32 v145, v103, v145
	v_cvt_pk_bf16_f32 v142, v105, v107
	v_add_u32_e32 v105, s92, v130
	v_mfma_f32_32x32x16_bf16 v[0:15], v[70:73], v[86:89], v[0:15]
	v_mul_f32_e32 v146, v103, v146
	v_mul_f32_e32 v147, v103, v147
	v_cvt_pk_bf16_f32 v143, v148, v143
	v_cvt_pk_bf16_f32 v144, v144, v145
	v_cvt_pk_bf16_f32 v145, v146, v147
	s_waitcnt vmcnt(18)
	v_and_b32_e32 v107, 0xffff0000, v38
	v_lshlrev_b32_e32 v146, 16, v41
	v_mfma_f32_32x32x16_bf16 v[0:15], v[66:69], v[82:85], v[0:15]
	ds_read_b64_tr_b16 v[90:91], v134 offset:0
	ds_read_b64_tr_b16 v[92:93], v134 offset:1088
	ds_read_b64_tr_b16 v[82:83], v134 offset:4352
	ds_read_b64_tr_b16 v[84:85], v134 offset:5440
	ds_read_b64_tr_b16 v[74:75], v134 offset:8704
	ds_read_b64_tr_b16 v[76:77], v134 offset:9792
	ds_read_b64_tr_b16 v[66:67], v134 offset:13056
	ds_read_b64_tr_b16 v[68:69], v134 offset:14144
	s_waitcnt lgkmcnt(0)
	ds_read_b64_tr_b16 v[94:95], v135 offset:0
	ds_read_b64_tr_b16 v[96:97], v135 offset:1088
	ds_read_b64_tr_b16 v[86:87], v135 offset:4352
	ds_read_b64_tr_b16 v[88:89], v135 offset:5440
	ds_read_b64_tr_b16 v[78:79], v135 offset:8704
	ds_read_b64_tr_b16 v[80:81], v135 offset:9792
	ds_read_b64_tr_b16 v[70:71], v135 offset:13056
	ds_read_b64_tr_b16 v[72:73], v135 offset:14144
	s_waitcnt lgkmcnt(0)
	ds_write_b128 v105, v[142:145]
	v_lshlrev_b32_e32 v105, 16, v38
	v_lshlrev_b32_e32 v142, 16, v39
	v_and_b32_e32 v143, 0xffff0000, v39
	v_lshlrev_b32_e32 v144, 16, v40
	v_mfma_f32_32x32x16_bf16 v[0:15], v[90:93], v[94:97], v[0:15]
	v_and_b32_e32 v145, 0xffff0000, v40
	v_mul_f32_e32 v105, v139, v105
	v_and_b32_e32 v147, 0xffff0000, v41
	v_mul_f32_e32 v107, v139, v107
	v_mul_f32_e32 v148, v139, v142
	v_mul_f32_e32 v143, v139, v143
	v_mul_f32_e32 v144, v139, v144
	v_mfma_f32_32x32x16_bf16 v[0:15], v[82:85], v[86:89], v[0:15]
	v_mul_f32_e32 v145, v139, v145
	v_cvt_pk_bf16_f32 v142, v105, v107
	v_add_u32_e32 v105, s92, v131
	v_mul_f32_e32 v146, v139, v146
	v_mul_f32_e32 v147, v139, v147
	v_cvt_pk_bf16_f32 v143, v148, v143
	v_cvt_pk_bf16_f32 v144, v144, v145
	v_mfma_f32_32x32x16_bf16 v[0:15], v[74:77], v[78:81], v[0:15]
	v_cvt_pk_bf16_f32 v145, v146, v147
	ds_write_b128 v105, v[142:145]
	s_waitcnt vmcnt(17)
	v_lshlrev_b32_e32 v105, 16, v50
	v_and_b32_e32 v107, 0xffff0000, v50
	v_lshlrev_b32_e32 v142, 16, v51
	v_and_b32_e32 v143, 0xffff0000, v51
	v_lshlrev_b32_e32 v144, 16, v52
	v_mfma_f32_32x32x16_bf16 v[0:15], v[66:69], v[70:73], v[0:15]
	v_and_b32_e32 v145, 0xffff0000, v52
	v_mul_f32_e32 v105, v140, v105
	v_lshlrev_b32_e32 v146, 16, v53
	v_and_b32_e32 v147, 0xffff0000, v53
	v_mul_f32_e32 v107, v140, v107
	v_mul_f32_e32 v148, v140, v142
	v_mul_f32_e32 v143, v140, v143
	v_mul_f32_e32 v144, v140, v144
	v_mul_f32_e32 v145, v140, v145
	v_cvt_pk_bf16_f32 v142, v105, v107
	v_add_u32_e32 v105, s92, v132
	v_mul_f32_e32 v146, v140, v146
	v_mul_f32_e32 v147, v140, v147
	v_cvt_pk_bf16_f32 v143, v148, v143
	v_cvt_pk_bf16_f32 v144, v144, v145
	v_cvt_pk_bf16_f32 v145, v146, v147
	ds_write_b128 v105, v[142:145]
	s_waitcnt vmcnt(16)
	v_lshlrev_b32_e32 v105, 16, v54
	v_and_b32_e32 v107, 0xffff0000, v54
	v_lshlrev_b32_e32 v142, 16, v55
	v_and_b32_e32 v143, 0xffff0000, v55
	v_lshlrev_b32_e32 v144, 16, v56
	v_and_b32_e32 v145, 0xffff0000, v56
	v_mul_f32_e32 v105, v141, v105
	v_lshlrev_b32_e32 v146, 16, v57
	v_and_b32_e32 v147, 0xffff0000, v57
	v_mul_f32_e32 v107, v141, v107
	v_mul_f32_e32 v148, v141, v142
	v_mul_f32_e32 v143, v141, v143
	v_mul_f32_e32 v144, v141, v144
	v_mul_f32_e32 v145, v141, v145
	v_cvt_pk_bf16_f32 v142, v105, v107
	v_add_u32_e32 v105, s92, v133
	v_mul_f32_e32 v146, v141, v146
	v_mul_f32_e32 v147, v141, v147
	v_cvt_pk_bf16_f32 v143, v148, v143
	v_cvt_pk_bf16_f32 v144, v144, v145
	v_cvt_pk_bf16_f32 v145, v146, v147
	ds_write_b128 v105, v[142:145]
	v_add_u32_e32 v105, 0x19800, v138
	s_cmp_gt_u32 s15, 12
	s_waitcnt vmcnt(15)
	ds_write_b128 v105, v[58:61]
	s_waitcnt vmcnt(14)
	ds_write_b128 v105, v[62:65] offset:17408
	s_waitcnt lgkmcnt(0)
	s_barrier
	s_and_b64 s[16:17], s[6:7], exec
	s_cselect_b32 s16, s12, s13
	s_min_i32 s16, s16, 15
	s_max_i32 s16, s16, 0
	s_mul_i32 s88, s16, 0x160000
	v_lshl_add_u64 v[50:51], v[108:109], 0, s[88:89]
	v_add_co_u32_e32 v38, vcc, 0x58000, v50
	v_lshl_add_u64 v[58:59], v[110:111], 0, s[88:89]
	s_nop 0
	v_addc_co_u32_e32 v39, vcc, 0, v51, vcc
	v_add_co_u32_e32 v52, vcc, 0xb0000, v50
	global_load_dwordx4 v[34:37], v[50:51], off
	s_nop 0
	global_load_dwordx4 v[38:41], v[38:39], off
	v_addc_co_u32_e32 v53, vcc, 0, v51, vcc
	v_add_co_u32_e32 v54, vcc, 0x108000, v50
	s_nop 1
	v_addc_co_u32_e32 v55, vcc, 0, v51, vcc
	v_add_co_u32_e32 v62, vcc, 0xb0000, v58
	global_load_dwordx4 v[50:53], v[52:53], off
	s_nop 0
	global_load_dwordx4 v[54:57], v[54:55], off
	v_addc_co_u32_e32 v63, vcc, 0, v59, vcc
	global_load_dwordx4 v[58:61], v[58:59], off
	s_nop 0
	global_load_dwordx4 v[62:65], v[62:63], off
	s_branch .LBB0_711
